# diff attention VALU diet: V tile stored in natural key order + P fed unswapped (8 permlane swaps gone), saddr tile loads, NaN-canonicalising maxes removed, defer-max common/rare path split
# speedup vs baseline: 1.0143x; 1.0081x over previous
.LBB0_396:
	s_or_b32 s4, s4, s90
	s_mul_i32 s4, s4, 0x102000
	s_add_i32 s44, s91, s4
	s_xor_b64 s[50:51], s[52:53], -1
	v_mbcnt_lo_u32_b32 v32, -1, 0
	v_mbcnt_hi_u32_b32 v32, -1, v32
	s_lshl_b64 s[54:55], s[44:45], 1
	v_and_b32_e32 v198, 31, v32
	s_add_u32 s54, s26, s54
	v_or_b32_e32 v184, s40, v198
	v_bfe_u32 v199, v32, 5, 1
	s_addc_u32 s55, s27, s55
	v_lshlrev_b64 v[0:1], 8, v[184:185]
	v_lshl_add_u64 v[0:1], s[54:55], 0, v[0:1]
	v_lshlrev_b32_e32 v184, 4, v199
	v_lshl_add_u64 v[28:29], v[0:1], 0, v[184:185]
	global_load_dwordx4 v[0:3], v[28:29], off
	global_load_dwordx4 v[4:7], v[28:29], off offset:32
	global_load_dwordx4 v[8:11], v[28:29], off offset:64
	global_load_dwordx4 v[12:15], v[28:29], off offset:96
	global_load_dwordx4 v[16:19], v[28:29], off offset:128
	global_load_dwordx4 v[20:23], v[28:29], off offset:160
	global_load_dwordx4 v[24:27], v[28:29], off offset:192
	s_nop 0
	global_load_dwordx4 v[28:31], v[28:29], off offset:224
	v_add_u32_e32 v40, s64, v32
	v_and_b32_e32 v195, 63, v32
	v_lshlrev_b32_e32 v41, 3, v32
	s_mov_b32 s5, s45
	v_lshlrev_b32_e32 v34, 1, v32
	v_ashrrev_i32_e32 v42, 4, v40
	v_and_b32_e32 v43, 0x78, v41
	v_lshlrev_b32_e32 v196, 4, v195
	v_lshlrev_b32_e32 v36, 4, v32
	v_lshlrev_b32_e32 v197, 3, v195
	v_and_b32_e32 v37, 32, v34
	v_and_b32_e32 v34, 0xc0, v196
	v_lshl_or_b32 v32, v42, 7, v43
	s_lshl_b64 s[4:5], s[4:5], 1
	v_mov_b32_e32 v35, v185
	v_lshlrev_b32_e32 v44, 8, v198
	v_and_or_b32 v39, v197, 24, v34
	v_add_u32_e32 v34, 0x1000, v32
	s_add_u32 s4, s26, s4
	v_mov_b32_e32 v33, v185
	v_and_b32_e32 v45, 0x70, v36
	v_and_b32_e32 v38, 0x100, v197
	v_add_u32_e32 v46, s9, v44
	v_bitop3_b32 v36, v184, v36, s71 bitop3:0x78
	v_lshlrev_b64 v[188:189], 1, v[34:35]
	s_addc_u32 s5, s27, s5
	v_lshlrev_b64 v[186:187], 1, v[32:33]
	v_or3_b32 v56, v39, v37, v38
	v_add_u32_e32 v57, v46, v36
	v_lshl_add_u64 v[36:37], s[6:7], 0, v[188:189]
	s_add_u32 s54, s4, 0x4080000
	v_lshl_add_u64 v[32:33], s[6:7], 0, v[186:187]
	v_lshl_add_u64 v[34:35], s[48:49], 0, v[186:187]
	v_lshl_add_u64 v[38:39], s[48:49], 0, v[188:189]
	global_load_dwordx4 v[180:183], v[36:37], off
	global_load_dwordx4 v[176:179], v[32:33], off
	global_load_dwordx4 v[164:167], v[38:39], off
	global_load_dwordx4 v[160:163], v[34:35], off
	s_addc_u32 s55, s5, 0
	v_lshl_add_u64 v[32:33], s[54:55], 0, v[188:189]
	v_lshl_add_u64 v[34:35], s[54:55], 0, v[186:187]
	global_load_dwordx4 v[172:175], v[32:33], off
	global_load_dwordx4 v[168:171], v[34:35], off
	s_movk_i32 s14, 0x60
	v_bitop3_b32 v48, v184, v45, 32 bitop3:0x36
	v_bitop3_b32 v50, v184, v45, 64 bitop3:0x36
	v_bitop3_b32 v52, v184, v45, s14 bitop3:0x36
	v_or_b32_e32 v53, 0x80, v184
	v_or_b32_e32 v54, 0xa0, v184
	v_or_b32_e32 v55, 0xc0, v184
	v_add_u32_e32 v48, v46, v48
	v_add_u32_e32 v50, v46, v50
	v_add_u32_e32 v52, v46, v52
	v_xad_u32 v53, v53, v45, v46
	v_xad_u32 v54, v54, v45, v46
	v_xad_u32 v55, v55, v45, v46
	s_cmp_lg_u32 0, -1
	s_cselect_b32 s4, 0, 0
	v_add_u32_e32 v200, s4, v56
	s_add_i32 s4, 0, 0x8000
	s_cmp_lg_u32 s4, -1
	v_or_b32_e32 v47, 32, v184
	s_cselect_b32 s4, s4, 0
	v_or_b32_e32 v49, 64, v184
	v_or_b32_e32 v51, 0x60, v184
	v_mov_b32_e32 v64, v185
	v_mov_b32_e32 v65, v185
	v_mov_b32_e32 v78, v185
	v_mov_b32_e32 v79, v185
	v_mov_b32_e32 v66, v185
	v_mov_b32_e32 v67, v185
	v_mov_b32_e32 v68, v185
	v_mov_b32_e32 v69, v185
	v_mov_b32_e32 v70, v185
	v_mov_b32_e32 v71, v185
	s_waitcnt vmcnt(13)
	ds_write_b128 v57, v[0:3] offset:49152
	s_waitcnt vmcnt(12)
	ds_write_b128 v48, v[4:7] offset:49152
	s_waitcnt vmcnt(11)
	ds_write_b128 v50, v[8:11] offset:49152
	s_waitcnt vmcnt(10)
	ds_write_b128 v52, v[12:15] offset:49152
	s_waitcnt vmcnt(9)
	ds_write_b128 v53, v[16:19] offset:49152
	s_waitcnt vmcnt(8)
	ds_write_b128 v54, v[20:23] offset:49152
	s_waitcnt vmcnt(7)
	ds_write_b128 v55, v[24:27] offset:49152
	v_lshrrev_b32_e32 v4, 1, v42
	v_and_b32_e32 v5, 3, v42
	v_and_or_b32 v4, v4, 4, v5
	v_add_u32_e32 v5, 32, v42
	v_lshlrev_b32_e32 v2, 1, v42
	v_and_b32_e32 v3, 0xfffff0, v42
	v_lshlrev_b32_e32 v6, 1, v5
	v_and_b32_e32 v5, 0xfffff0, v5
	v_or_b32_e32 v0, 0xe0, v184
	v_and_or_b32 v2, v2, 8, v3
	v_and_or_b32 v5, v6, 8, v5
	v_xad_u32 v0, v0, v45, v46
	v_lshrrev_b32_e32 v2, 1, v2
	v_bfe_u32 v3, v41, 5, 2
	v_lshrrev_b32_e32 v5, 1, v5
	s_waitcnt vmcnt(6)
	ds_write_b128 v0, v[28:31] offset:49152
	v_lshlrev_b32_e32 v0, 1, v43
	v_or_b32_e32 v2, v2, v3
	v_or_b32_e32 v3, v5, v3
	v_bitop3_b32 v1, v0, v40, s71 bitop3:0x78
	v_lshlrev_b32_e32 v2, 9, v2
	v_lshlrev_b32_e32 v4, 6, v4
	v_and_b32_e32 v0, 48, v0
	v_lshlrev_b32_e32 v3, 9, v3
	v_or3_b32 v2, v2, v4, v0
	v_or3_b32 v0, v3, v4, v0
	v_bitop3_b32 v4, v184, v44, v45 bitop3:0xde
	v_add_u32_e32 v201, s4, v4
	v_add_u32_e32 v202, s61, v4
	v_bitop3_b32 v4, v47, v44, v45 bitop3:0xde
	v_add_u32_e32 v203, s4, v4
	v_add_u32_e32 v204, s61, v4
	v_bitop3_b32 v4, v49, v44, v45 bitop3:0xde
	v_lshl_add_u32 v3, v42, 8, 0
	v_add_u32_e32 v206, s4, v4
	v_add_u32_e32 v207, s61, v4
	v_bitop3_b32 v4, v51, v44, v45 bitop3:0xde
	v_add_u32_e32 v208, s4, v4
	v_add_u32_e32 v209, s61, v4
	v_mov_b32_e32 v72, v185
	v_mov_b32_e32 v73, v185
	v_mov_b32_e32 v74, v185
	v_mov_b32_e32 v75, v185
	v_mov_b32_e32 v76, v185
	v_mov_b32_e32 v77, v185
	v_add_u32_e32 v211, v3, v1
	v_lshrrev_b32_e32 v243, 3, v42
	v_bfe_u32 v244, v41, 5, 2
	v_lshl_or_b32 v243, v243, 2, v244
	v_lshlrev_b32_e32 v243, 9, v243
	v_and_b32_e32 v244, 7, v42
	v_lshl_or_b32 v243, v244, 6, v243
	v_lshlrev_b32_e32 v244, 1, v43
	v_and_b32_e32 v244, 48, v244
	v_or_b32_e32 v212, v243, v244
	v_add_u32_e32 v213, 0x2000, v212
	v_mov_b64_e32 v[126:127], v[78:79]
	v_mov_b64_e32 v[110:111], v[78:79]
	v_mov_b64_e32 v[94:95], v[78:79]
	v_mov_b64_e32 v[48:49], v[64:65]
	v_mov_b64_e32 v[32:33], v[64:65]
	v_mov_b64_e32 v[16:17], v[64:65]
	v_mov_b64_e32 v[0:1], v[64:65]
	s_mov_b32 s44, 64
	v_cmp_gt_u32_e64 s[4:5], 32, v195
	v_lshl_add_u32 v205, v198, 2, s63
	v_mov_b32_e32 v214, 0
	v_mov_b32_e32 v210, 0xf149f2ca
	v_mov_b64_e32 v[124:125], v[76:77]
	v_mov_b64_e32 v[122:123], v[74:75]
	v_mov_b64_e32 v[120:121], v[72:73]
	v_mov_b64_e32 v[118:119], v[70:71]
	v_mov_b64_e32 v[116:117], v[68:69]
	v_mov_b64_e32 v[114:115], v[66:67]
	v_mov_b64_e32 v[112:113], v[64:65]
	v_mov_b64_e32 v[108:109], v[76:77]
	v_mov_b64_e32 v[106:107], v[74:75]
	v_mov_b64_e32 v[104:105], v[72:73]
	v_mov_b64_e32 v[102:103], v[70:71]
	v_mov_b64_e32 v[100:101], v[68:69]
	v_mov_b64_e32 v[98:99], v[66:67]
	v_mov_b64_e32 v[96:97], v[64:65]
	v_mov_b64_e32 v[92:93], v[76:77]
	v_mov_b64_e32 v[90:91], v[74:75]
	v_mov_b64_e32 v[88:89], v[72:73]
	v_mov_b64_e32 v[86:87], v[70:71]
	v_mov_b64_e32 v[84:85], v[68:69]
	v_mov_b64_e32 v[82:83], v[66:67]
	v_mov_b64_e32 v[80:81], v[64:65]
	v_mov_b64_e32 v[50:51], v[66:67]
	v_mov_b64_e32 v[52:53], v[68:69]
	v_mov_b64_e32 v[54:55], v[70:71]
	v_mov_b64_e32 v[56:57], v[72:73]
	v_mov_b64_e32 v[58:59], v[74:75]
	v_mov_b64_e32 v[60:61], v[76:77]
	v_mov_b64_e32 v[62:63], v[78:79]
	v_mov_b64_e32 v[34:35], v[66:67]
	v_mov_b64_e32 v[36:37], v[68:69]
	v_mov_b64_e32 v[38:39], v[70:71]
	v_mov_b64_e32 v[40:41], v[72:73]
	v_mov_b64_e32 v[42:43], v[74:75]
	v_mov_b64_e32 v[44:45], v[76:77]
	v_mov_b64_e32 v[46:47], v[78:79]
	v_mov_b64_e32 v[18:19], v[66:67]
	v_mov_b64_e32 v[20:21], v[68:69]
	v_mov_b64_e32 v[22:23], v[70:71]
	v_mov_b64_e32 v[24:25], v[72:73]
	v_mov_b64_e32 v[26:27], v[74:75]
	v_mov_b64_e32 v[28:29], v[76:77]
	v_mov_b64_e32 v[30:31], v[78:79]
	v_mov_b64_e32 v[2:3], v[66:67]
	v_mov_b64_e32 v[4:5], v[68:69]
	v_mov_b64_e32 v[6:7], v[70:71]
	v_mov_b64_e32 v[8:9], v[72:73]
	v_mov_b64_e32 v[10:11], v[74:75]
	v_mov_b64_e32 v[12:13], v[76:77]
	v_mov_b64_e32 v[14:15], v[78:79]
	s_mov_b32 s56, 0
.LBB0_397:
	s_waitcnt vmcnt(0)
	s_add_i32 s96, s56, 1
	s_cmp_ge_i32 s96, s93
	s_waitcnt lgkmcnt(0)
	s_barrier
	s_waitcnt vmcnt(0)
	ds_write_b128 v211, v[168:171] offset:32768
	ds_write_b128 v211, v[172:175] offset:40960
	ds_write_b128 v212, v[160:163]
	ds_write_b128 v213, v[164:167]
	ds_write_b128 v212, v[176:179] offset:16384
	ds_write_b128 v213, v[180:183] offset:16384
	s_waitcnt lgkmcnt(0)
	s_barrier
	s_cbranch_scc1 .LBB0_399
	s_lshl_b64 vcc, s[44:45], 8
	s_add_u32 s24, s54, vcc_lo
	s_addc_u32 s25, s55, vcc_hi
	s_add_u32 s14, s48, vcc_lo
	s_addc_u32 s15, s49, vcc_hi
	global_load_dwordx4 v[168:171], v186, s[24:25]
	global_load_dwordx4 v[172:175], v188, s[24:25]
	global_load_dwordx4 v[160:163], v186, s[14:15]
	global_load_dwordx4 v[164:167], v188, s[14:15]
	s_add_u32 s24, s6, vcc_lo
	s_addc_u32 s25, s7, vcc_hi
	global_load_dwordx4 v[176:179], v186, s[24:25]
	global_load_dwordx4 v[180:183], v188, s[24:25]
.LBB0_399:
	s_cmp_ge_i32 s56, s94
	s_cbranch_scc1 .LBB0_405
	ds_read_b128 v[144:147], v202 offset:0
	ds_read_b128 v[128:131], v201 offset:0
	ds_read_b128 v[148:151], v201 offset:0x2000
	ds_read_b128 v[216:219], v204 offset:0
	ds_read_b128 v[220:223], v203 offset:0
	ds_read_b128 v[224:227], v203 offset:0x2000
	s_waitcnt lgkmcnt(3)
	s_nop 0
	v_mfma_f32_32x32x16_bf16 v[128:143], v[128:131], v[144:147], 0
	v_mfma_f32_32x32x16_bf16 v[144:159], v[148:151], v[144:147], 0
	ds_read_b128 v[228:231], v207 offset:0
	ds_read_b128 v[232:235], v206 offset:0
	ds_read_b128 v[236:239], v206 offset:0x2000
	s_waitcnt lgkmcnt(3)
	v_mfma_f32_32x32x16_bf16 v[128:143], v[220:223], v[216:219], v[128:143]
	v_mfma_f32_32x32x16_bf16 v[144:159], v[224:227], v[216:219], v[144:159]
	ds_read_b128 v[216:219], v209 offset:0
	ds_read_b128 v[220:223], v208 offset:0
	ds_read_b128 v[224:227], v208 offset:0x2000
	s_waitcnt lgkmcnt(3)
	v_mfma_f32_32x32x16_bf16 v[128:143], v[232:235], v[228:231], v[128:143]
	v_mfma_f32_32x32x16_bf16 v[144:159], v[236:239], v[228:231], v[144:159]
	ds_read_b128 v[228:231], v202 offset:0x80
	ds_read_b128 v[232:235], v201 offset:0x80
	ds_read_b128 v[236:239], v201 offset:0x2080
	s_waitcnt lgkmcnt(3)
	v_mfma_f32_32x32x16_bf16 v[128:143], v[220:223], v[216:219], v[128:143]
	v_mfma_f32_32x32x16_bf16 v[144:159], v[224:227], v[216:219], v[144:159]
	ds_read_b128 v[216:219], v204 offset:0x80
	ds_read_b128 v[220:223], v203 offset:0x80
	ds_read_b128 v[224:227], v203 offset:0x2080
	s_waitcnt lgkmcnt(3)
	v_mfma_f32_32x32x16_bf16 v[128:143], v[232:235], v[228:231], v[128:143]
	v_mfma_f32_32x32x16_bf16 v[144:159], v[236:239], v[228:231], v[144:159]
	ds_read_b128 v[228:231], v207 offset:0x80
	ds_read_b128 v[232:235], v206 offset:0x80
	ds_read_b128 v[236:239], v206 offset:0x2080
	s_waitcnt lgkmcnt(3)
	v_mfma_f32_32x32x16_bf16 v[128:143], v[220:223], v[216:219], v[128:143]
	v_mfma_f32_32x32x16_bf16 v[144:159], v[224:227], v[216:219], v[144:159]
	ds_read_b128 v[216:219], v209 offset:0x80
	ds_read_b128 v[220:223], v208 offset:0x80
	ds_read_b128 v[224:227], v208 offset:0x2080
	s_waitcnt lgkmcnt(3)
	v_mfma_f32_32x32x16_bf16 v[128:143], v[232:235], v[228:231], v[128:143]
	v_mfma_f32_32x32x16_bf16 v[144:159], v[236:239], v[228:231], v[144:159]
	s_waitcnt lgkmcnt(0)
	v_mfma_f32_32x32x16_bf16 v[128:143], v[220:223], v[216:219], v[128:143]
	s_cmp_eq_u32 s56, 0
	s_cselect_b64 vcc, -1, 0
	s_mov_b32 s14, 0x41000000
	v_mfma_f32_32x32x16_bf16 v[144:159], v[224:227], v[216:219], v[144:159]
	s_cbranch_scc1 .Ldiff_pad
	s_nop 7
	v_max_f32_e32 v215, v128, v129
	v_max3_f32 v215, v215, v130, v131
	v_max3_f32 v215, v215, v132, v133
	v_max3_f32 v215, v215, v134, v135
	v_max3_f32 v215, v215, v136, v137
	v_max3_f32 v215, v215, v138, v139
	v_max3_f32 v215, v215, v140, v141
	v_max3_f32 v215, v215, v142, v143
	v_max3_f32 v215, v215, v144, v145
	v_max3_f32 v215, v215, v146, v147
	v_max3_f32 v215, v215, v148, v149
	v_max3_f32 v215, v215, v150, v151
	v_max3_f32 v215, v215, v152, v153
	v_max3_f32 v215, v215, v154, v155
	v_max3_f32 v215, v215, v156, v157
	v_max3_f32 v215, v215, v158, v159
	s_branch .Ldiff_padjoin
.Ldiff_pad:
	s_nop 7
	v_max_f32_e32 v215, v128, v129
	v_max3_f32 v215, v215, v130, v131
	v_max3_f32 v215, v215, v132, v133
	v_cndmask_b32_e32 v137, v137, v193, vcc
	v_cndmask_b32_e32 v136, v136, v193, vcc
	v_max3_f32 v215, v215, v134, v135
	v_cndmask_b32_e32 v139, v139, v193, vcc
	v_cndmask_b32_e32 v138, v138, v193, vcc
	v_max3_f32 v215, v215, v136, v137
	v_cndmask_b32_e32 v141, v141, v193, vcc
	v_cndmask_b32_e32 v140, v140, v193, vcc
	v_max3_f32 v215, v215, v138, v139
	v_cndmask_b32_e32 v143, v143, v193, vcc
	v_cndmask_b32_e32 v142, v142, v193, vcc
	v_max3_f32 v215, v215, v140, v141
	v_cndmask_b32_e32 v145, v145, v193, vcc
	v_cndmask_b32_e32 v144, v144, v193, vcc
	v_max3_f32 v215, v215, v142, v143
	v_cndmask_b32_e32 v147, v147, v193, vcc
	v_cndmask_b32_e32 v146, v146, v193, vcc
	v_max3_f32 v215, v215, v144, v145
	v_cndmask_b32_e32 v149, v149, v193, vcc
	v_cndmask_b32_e32 v148, v148, v193, vcc
	v_max3_f32 v215, v215, v146, v147
	v_cndmask_b32_e32 v151, v151, v193, vcc
	v_cndmask_b32_e32 v150, v150, v193, vcc
	v_max3_f32 v215, v215, v148, v149
	v_cndmask_b32_e32 v153, v153, v193, vcc
	v_cndmask_b32_e32 v152, v152, v193, vcc
	v_max3_f32 v215, v215, v150, v151
	v_cndmask_b32_e32 v155, v155, v193, vcc
	v_cndmask_b32_e32 v154, v154, v193, vcc
	v_max3_f32 v215, v215, v152, v153
	v_cndmask_b32_e32 v157, v157, v193, vcc
	v_cndmask_b32_e32 v156, v156, v193, vcc
	v_max3_f32 v215, v215, v154, v155
	v_cndmask_b32_e32 v159, v159, v193, vcc
	v_cndmask_b32_e32 v158, v158, v193, vcc
	v_max3_f32 v215, v215, v156, v157
	v_max3_f32 v215, v215, v158, v159
.Ldiff_padjoin:
	v_mov_b32_e32 v216, v215
	s_nop 1
	v_permlane32_swap_b32_e32 v215, v216
	v_max_f32_e32 v215, v215, v216
	v_sub_f32_e32 v216, v215, v210
	v_mul_f32_e32 v216, 0x3db504f3, v216
	v_cmp_ge_f32_e32 vcc, s14, v216
	v_mul_f32_e32 v216, 0xbe0293ee, v210
	s_cmp_eq_u64 vcc, exec
	s_cbranch_scc0 .Ldiff_sm_rare
	v_fmamk_f32 v128, v128, 0x3e0293ee, v216
	v_fmamk_f32 v129, v129, 0x3e0293ee, v216
	v_exp_f32_e32 v128, v128
	v_fmamk_f32 v130, v130, 0x3e0293ee, v216
	v_exp_f32_e32 v129, v129
	v_fmamk_f32 v131, v131, 0x3e0293ee, v216
	v_exp_f32_e32 v130, v130
	v_fmamk_f32 v132, v132, 0x3e0293ee, v216
	v_fmamk_f32 v133, v133, 0x3e0293ee, v216
	v_fmamk_f32 v134, v134, 0x3e0293ee, v216
	v_fmamk_f32 v135, v135, 0x3e0293ee, v216
	v_fmamk_f32 v136, v136, 0x3e0293ee, v216
	v_fmamk_f32 v137, v137, 0x3e0293ee, v216
	v_fmamk_f32 v138, v138, 0x3e0293ee, v216
	v_fmamk_f32 v139, v139, 0x3e0293ee, v216
	v_fmamk_f32 v140, v140, 0x3e0293ee, v216
	v_fmamk_f32 v141, v141, 0x3e0293ee, v216
	v_fmamk_f32 v142, v142, 0x3e0293ee, v216
	v_fmamk_f32 v143, v143, 0x3e0293ee, v216
	v_fmamk_f32 v144, v144, 0x3e0293ee, v216
	v_fmamk_f32 v145, v145, 0x3e0293ee, v216
	v_fmamk_f32 v146, v146, 0x3e0293ee, v216
	v_fmamk_f32 v147, v147, 0x3e0293ee, v216
	v_fmamk_f32 v148, v148, 0x3e0293ee, v216
	v_fmamk_f32 v149, v149, 0x3e0293ee, v216
	v_fmamk_f32 v150, v150, 0x3e0293ee, v216
	v_fmamk_f32 v151, v151, 0x3e0293ee, v216
	v_fmamk_f32 v152, v152, 0x3e0293ee, v216
	v_fmamk_f32 v153, v153, 0x3e0293ee, v216
	v_fmamk_f32 v154, v154, 0x3e0293ee, v216
	v_fmamk_f32 v155, v155, 0x3e0293ee, v216
	v_fmamk_f32 v156, v156, 0x3e0293ee, v216
	v_fmamk_f32 v157, v157, 0x3e0293ee, v216
	v_fmamk_f32 v158, v158, 0x3e0293ee, v216
	v_fmac_f32_e32 v216, 0x3e0293ee, v159
	v_exp_f32_e32 v131, v131
	v_exp_f32_e32 v132, v132
	v_exp_f32_e32 v159, v216
	v_add_f32_e32 v216, 0, v128
	v_exp_f32_e32 v133, v133
	v_add_f32_e32 v216, v129, v216
	v_exp_f32_e32 v134, v134
	v_add_f32_e32 v216, v130, v216
	v_exp_f32_e32 v135, v135
	v_add_f32_e32 v216, v131, v216
	v_exp_f32_e32 v136, v136
	v_add_f32_e32 v216, v132, v216
	v_exp_f32_e32 v137, v137
	v_add_f32_e32 v216, v133, v216
	v_exp_f32_e32 v138, v138
	v_add_f32_e32 v216, v134, v216
	v_exp_f32_e32 v139, v139
	v_add_f32_e32 v216, v135, v216
	v_exp_f32_e32 v140, v140
	v_add_f32_e32 v216, v136, v216
	v_exp_f32_e32 v141, v141
	v_add_f32_e32 v216, v137, v216
	v_exp_f32_e32 v142, v142
	v_add_f32_e32 v216, v138, v216
	v_exp_f32_e32 v143, v143
	v_add_f32_e32 v216, v139, v216
	v_exp_f32_e32 v144, v144
	v_add_f32_e32 v216, v140, v216
	v_exp_f32_e32 v145, v145
	v_add_f32_e32 v216, v141, v216
	v_exp_f32_e32 v146, v146
	v_add_f32_e32 v216, v142, v216
	v_exp_f32_e32 v147, v147
	v_add_f32_e32 v216, v143, v216
	v_exp_f32_e32 v148, v148
	v_add_f32_e32 v216, v144, v216
	v_exp_f32_e32 v149, v149
	v_add_f32_e32 v216, v145, v216
	v_exp_f32_e32 v150, v150
	v_add_f32_e32 v216, v146, v216
	v_exp_f32_e32 v151, v151
	v_add_f32_e32 v216, v147, v216
	v_exp_f32_e32 v152, v152
	v_add_f32_e32 v216, v148, v216
	v_exp_f32_e32 v153, v153
	v_add_f32_e32 v216, v149, v216
	v_exp_f32_e32 v154, v154
	v_add_f32_e32 v216, v150, v216
	v_exp_f32_e32 v155, v155
	v_add_f32_e32 v216, v151, v216
	v_exp_f32_e32 v156, v156
	v_add_f32_e32 v216, v152, v216
	v_exp_f32_e32 v157, v157
	v_add_f32_e32 v216, v153, v216
	v_exp_f32_e32 v158, v158
	v_add_f32_e32 v216, v154, v216
	v_add_f32_e32 v216, v155, v216
	v_add_f32_e32 v216, v156, v216
	v_add_f32_e32 v216, v157, v216
	v_add_f32_e32 v216, v158, v216
	v_add_f32_e32 v216, v159, v216
	v_mov_b32_e32 v217, v216
	v_cvt_pk_bf16_f32 v128, v128, v129
	v_cvt_pk_bf16_f32 v129, v130, v131
	v_cvt_pk_bf16_f32 v130, v132, v133
	v_cvt_pk_bf16_f32 v131, v134, v135
	v_cvt_pk_bf16_f32 v132, v136, v137
	v_cvt_pk_bf16_f32 v133, v138, v139
	v_cvt_pk_bf16_f32 v134, v140, v141
	v_cvt_pk_bf16_f32 v135, v142, v143
	v_cvt_pk_bf16_f32 v136, v144, v145
	v_cvt_pk_bf16_f32 v137, v146, v147
	v_cvt_pk_bf16_f32 v138, v148, v149
	v_cvt_pk_bf16_f32 v139, v150, v151
	v_cvt_pk_bf16_f32 v140, v152, v153
	v_cvt_pk_bf16_f32 v141, v154, v155
	v_cvt_pk_bf16_f32 v142, v156, v157
	v_cvt_pk_bf16_f32 v143, v158, v159
	s_nop 1
	v_permlane32_swap_b32_e32 v216, v217
	v_add_f32_e32 v230, v216, v217
	v_add_f32_e32 v230, v214, v230
.Ldiff_sm_join:
	ds_read_b64_tr_b16 v[144:145], v200 offset:0
	ds_read_b64_tr_b16 v[146:147], v200 offset:0x800
	ds_read_b64_tr_b16 v[148:149], v200 offset:0x1000
	ds_read_b64_tr_b16 v[150:151], v200 offset:0x1800
	ds_read_b64_tr_b16 v[152:153], v200 offset:0x2000
	ds_read_b64_tr_b16 v[154:155], v200 offset:0x2800
	ds_read_b64_tr_b16 v[156:157], v200 offset:0x3000
	ds_read_b64_tr_b16 v[158:159], v200 offset:0x3800
	s_waitcnt lgkmcnt(0)
	ds_read_b64_tr_b16 v[214:215], v200 offset:0x200
	ds_read_b64_tr_b16 v[216:217], v200 offset:0xa00
	ds_read_b64_tr_b16 v[218:219], v200 offset:0x1200
	ds_read_b64_tr_b16 v[220:221], v200 offset:0x1a00
	ds_read_b64_tr_b16 v[222:223], v200 offset:0x2200
	ds_read_b64_tr_b16 v[224:225], v200 offset:0x2a00
	ds_read_b64_tr_b16 v[226:227], v200 offset:0x3200
	ds_read_b64_tr_b16 v[228:229], v200 offset:0x3a00
	s_nop 0
	v_mfma_f32_32x32x16_bf16 v[64:79], v[128:131], v[144:147], v[64:79]
	v_mfma_f32_32x32x16_bf16 v[64:79], v[132:135], v[148:151], v[64:79]
	v_mfma_f32_32x32x16_bf16 v[64:79], v[136:139], v[152:155], v[64:79]
	v_mfma_f32_32x32x16_bf16 v[64:79], v[140:143], v[156:159], v[64:79]
	s_waitcnt lgkmcnt(0)
	ds_read_b64_tr_b16 v[144:145], v200 offset:0x400
	ds_read_b64_tr_b16 v[146:147], v200 offset:0xc00
	ds_read_b64_tr_b16 v[148:149], v200 offset:0x1400
	ds_read_b64_tr_b16 v[150:151], v200 offset:0x1c00
	ds_read_b64_tr_b16 v[152:153], v200 offset:0x2400
	ds_read_b64_tr_b16 v[154:155], v200 offset:0x2c00
	ds_read_b64_tr_b16 v[156:157], v200 offset:0x3400
	ds_read_b64_tr_b16 v[158:159], v200 offset:0x3c00
	v_mfma_f32_32x32x16_bf16 v[112:127], v[128:131], v[214:217], v[112:127]
	v_mfma_f32_32x32x16_bf16 v[112:127], v[132:135], v[218:221], v[112:127]
	v_mfma_f32_32x32x16_bf16 v[112:127], v[136:139], v[222:225], v[112:127]
	v_mfma_f32_32x32x16_bf16 v[112:127], v[140:143], v[226:229], v[112:127]
	s_waitcnt lgkmcnt(0)
	ds_read_b64_tr_b16 v[214:215], v200 offset:0x600
	ds_read_b64_tr_b16 v[216:217], v200 offset:0xe00
	ds_read_b64_tr_b16 v[218:219], v200 offset:0x1600
	ds_read_b64_tr_b16 v[220:221], v200 offset:0x1e00
	ds_read_b64_tr_b16 v[222:223], v200 offset:0x2600
	ds_read_b64_tr_b16 v[224:225], v200 offset:0x2e00
	ds_read_b64_tr_b16 v[226:227], v200 offset:0x3600
	ds_read_b64_tr_b16 v[228:229], v200 offset:0x3e00
	v_mfma_f32_32x32x16_bf16 v[96:111], v[128:131], v[144:147], v[96:111]
	v_mfma_f32_32x32x16_bf16 v[96:111], v[132:135], v[148:151], v[96:111]
	v_mfma_f32_32x32x16_bf16 v[96:111], v[136:139], v[152:155], v[96:111]
	v_mfma_f32_32x32x16_bf16 v[96:111], v[140:143], v[156:159], v[96:111]
	s_waitcnt lgkmcnt(0)
	ds_read_b64_tr_b16 v[144:145], v200 offset:0x4000
	ds_read_b64_tr_b16 v[146:147], v200 offset:0x4800
	ds_read_b64_tr_b16 v[148:149], v200 offset:0x5000
	ds_read_b64_tr_b16 v[150:151], v200 offset:0x5800
	ds_read_b64_tr_b16 v[152:153], v200 offset:0x6000
	ds_read_b64_tr_b16 v[154:155], v200 offset:0x6800
	ds_read_b64_tr_b16 v[156:157], v200 offset:0x7000
	ds_read_b64_tr_b16 v[158:159], v200 offset:0x7800
	v_mfma_f32_32x32x16_bf16 v[80:95], v[128:131], v[214:217], v[80:95]
	v_mfma_f32_32x32x16_bf16 v[80:95], v[132:135], v[218:221], v[80:95]
	v_mfma_f32_32x32x16_bf16 v[80:95], v[136:139], v[222:225], v[80:95]
	v_mfma_f32_32x32x16_bf16 v[80:95], v[140:143], v[226:229], v[80:95]
	s_waitcnt lgkmcnt(0)
	ds_read_b64_tr_b16 v[214:215], v200 offset:0x4200
	ds_read_b64_tr_b16 v[216:217], v200 offset:0x4a00
	ds_read_b64_tr_b16 v[218:219], v200 offset:0x5200
	ds_read_b64_tr_b16 v[220:221], v200 offset:0x5a00
	ds_read_b64_tr_b16 v[222:223], v200 offset:0x6200
	ds_read_b64_tr_b16 v[224:225], v200 offset:0x6a00
	ds_read_b64_tr_b16 v[226:227], v200 offset:0x7200
	ds_read_b64_tr_b16 v[228:229], v200 offset:0x7a00
	v_mfma_f32_32x32x16_bf16 v[48:63], v[128:131], v[144:147], v[48:63]
	v_mfma_f32_32x32x16_bf16 v[48:63], v[132:135], v[148:151], v[48:63]
	v_mfma_f32_32x32x16_bf16 v[48:63], v[136:139], v[152:155], v[48:63]
	v_mfma_f32_32x32x16_bf16 v[48:63], v[140:143], v[156:159], v[48:63]
	s_waitcnt lgkmcnt(0)
	ds_read_b64_tr_b16 v[144:145], v200 offset:0x4400
	ds_read_b64_tr_b16 v[146:147], v200 offset:0x4c00
	ds_read_b64_tr_b16 v[148:149], v200 offset:0x5400
	ds_read_b64_tr_b16 v[150:151], v200 offset:0x5c00
	ds_read_b64_tr_b16 v[152:153], v200 offset:0x6400
	ds_read_b64_tr_b16 v[154:155], v200 offset:0x6c00
	ds_read_b64_tr_b16 v[156:157], v200 offset:0x7400
	ds_read_b64_tr_b16 v[158:159], v200 offset:0x7c00
	v_mfma_f32_32x32x16_bf16 v[32:47], v[128:131], v[214:217], v[32:47]
	v_mfma_f32_32x32x16_bf16 v[32:47], v[132:135], v[218:221], v[32:47]
	v_mfma_f32_32x32x16_bf16 v[32:47], v[136:139], v[222:225], v[32:47]
	v_mfma_f32_32x32x16_bf16 v[32:47], v[140:143], v[226:229], v[32:47]
	s_waitcnt lgkmcnt(0)
	ds_read_b64_tr_b16 v[214:215], v200 offset:0x4600
	ds_read_b64_tr_b16 v[216:217], v200 offset:0x4e00
	ds_read_b64_tr_b16 v[218:219], v200 offset:0x5600
	ds_read_b64_tr_b16 v[220:221], v200 offset:0x5e00
	ds_read_b64_tr_b16 v[222:223], v200 offset:0x6600
	ds_read_b64_tr_b16 v[224:225], v200 offset:0x6e00
	ds_read_b64_tr_b16 v[226:227], v200 offset:0x7600
	ds_read_b64_tr_b16 v[228:229], v200 offset:0x7e00
	v_mfma_f32_32x32x16_bf16 v[16:31], v[128:131], v[144:147], v[16:31]
	v_mfma_f32_32x32x16_bf16 v[16:31], v[132:135], v[148:151], v[16:31]
	v_mfma_f32_32x32x16_bf16 v[16:31], v[136:139], v[152:155], v[16:31]
	v_mfma_f32_32x32x16_bf16 v[16:31], v[140:143], v[156:159], v[16:31]
	s_waitcnt lgkmcnt(0)
	v_mfma_f32_32x32x16_bf16 v[0:15], v[128:131], v[214:217], v[0:15]
	v_mov_b32_e32 v214, v230
	v_mfma_f32_32x32x16_bf16 v[0:15], v[132:135], v[218:221], v[0:15]
	v_mfma_f32_32x32x16_bf16 v[0:15], v[136:139], v[222:225], v[0:15]
	v_mfma_f32_32x32x16_bf16 v[0:15], v[140:143], v[226:229], v[0:15]

.Ldiff_sm_rare:
	v_max_f32_e32 v217, v210, v210
	v_max_f32_e32 v217, v217, v215
	s_cselect_b64 vcc, -1, 0
	v_sub_f32_e32 v215, v210, v217
	v_cndmask_b32_e32 v210, v217, v210, vcc
	v_mul_f32_e32 v216, 0xbe0293ee, v210
	v_fmamk_f32 v128, v128, 0x3e0293ee, v216
	v_fmamk_f32 v129, v129, 0x3e0293ee, v216
	v_exp_f32_e32 v128, v128
	v_fmamk_f32 v130, v130, 0x3e0293ee, v216
	v_exp_f32_e32 v129, v129
	v_fmamk_f32 v131, v131, 0x3e0293ee, v216
	v_exp_f32_e32 v130, v130
	v_fmamk_f32 v132, v132, 0x3e0293ee, v216
	v_fmamk_f32 v133, v133, 0x3e0293ee, v216
	v_fmamk_f32 v134, v134, 0x3e0293ee, v216
	v_fmamk_f32 v135, v135, 0x3e0293ee, v216
	v_fmamk_f32 v136, v136, 0x3e0293ee, v216
	v_fmamk_f32 v137, v137, 0x3e0293ee, v216
	v_fmamk_f32 v138, v138, 0x3e0293ee, v216
	v_fmamk_f32 v139, v139, 0x3e0293ee, v216
	v_fmamk_f32 v140, v140, 0x3e0293ee, v216
	v_fmamk_f32 v141, v141, 0x3e0293ee, v216
	v_fmamk_f32 v142, v142, 0x3e0293ee, v216
	v_fmamk_f32 v143, v143, 0x3e0293ee, v216
	v_fmamk_f32 v144, v144, 0x3e0293ee, v216
	v_fmamk_f32 v145, v145, 0x3e0293ee, v216
	v_fmamk_f32 v146, v146, 0x3e0293ee, v216
	v_fmamk_f32 v147, v147, 0x3e0293ee, v216
	v_fmamk_f32 v148, v148, 0x3e0293ee, v216
	v_fmamk_f32 v149, v149, 0x3e0293ee, v216
	v_fmamk_f32 v150, v150, 0x3e0293ee, v216
	v_fmamk_f32 v151, v151, 0x3e0293ee, v216
	v_fmamk_f32 v152, v152, 0x3e0293ee, v216
	v_fmamk_f32 v153, v153, 0x3e0293ee, v216
	v_fmamk_f32 v154, v154, 0x3e0293ee, v216
	v_fmamk_f32 v155, v155, 0x3e0293ee, v216
	v_fmamk_f32 v156, v156, 0x3e0293ee, v216
	v_fmamk_f32 v157, v157, 0x3e0293ee, v216
	v_fmamk_f32 v158, v158, 0x3e0293ee, v216
	v_fmac_f32_e32 v216, 0x3e0293ee, v159
	v_exp_f32_e32 v131, v131
	v_exp_f32_e32 v132, v132
	v_exp_f32_e32 v159, v216
	v_add_f32_e32 v216, 0, v128
	v_exp_f32_e32 v133, v133
	v_add_f32_e32 v216, v129, v216
	v_exp_f32_e32 v134, v134
	v_add_f32_e32 v216, v130, v216
	v_exp_f32_e32 v135, v135
	v_add_f32_e32 v216, v131, v216
	v_exp_f32_e32 v136, v136
	v_add_f32_e32 v216, v132, v216
	v_exp_f32_e32 v137, v137
	v_add_f32_e32 v216, v133, v216
	v_exp_f32_e32 v138, v138
	v_add_f32_e32 v216, v134, v216
	v_exp_f32_e32 v139, v139
	v_add_f32_e32 v216, v135, v216
	v_exp_f32_e32 v140, v140
	v_add_f32_e32 v216, v136, v216
	v_exp_f32_e32 v141, v141
	v_add_f32_e32 v216, v137, v216
	v_exp_f32_e32 v142, v142
	v_add_f32_e32 v216, v138, v216
	v_exp_f32_e32 v143, v143
	v_add_f32_e32 v216, v139, v216
	v_exp_f32_e32 v144, v144
	v_add_f32_e32 v216, v140, v216
	v_exp_f32_e32 v145, v145
	v_add_f32_e32 v216, v141, v216
	v_exp_f32_e32 v146, v146
	v_add_f32_e32 v216, v142, v216
	v_exp_f32_e32 v147, v147
	v_add_f32_e32 v216, v143, v216
	v_exp_f32_e32 v148, v148
	v_add_f32_e32 v216, v144, v216
	v_exp_f32_e32 v149, v149
	v_add_f32_e32 v216, v145, v216
	v_exp_f32_e32 v150, v150
	v_add_f32_e32 v216, v146, v216
	v_exp_f32_e32 v151, v151
	v_add_f32_e32 v216, v147, v216
	v_exp_f32_e32 v152, v152
	v_add_f32_e32 v216, v148, v216
	v_exp_f32_e32 v153, v153
	v_add_f32_e32 v216, v149, v216
	v_exp_f32_e32 v154, v154
	v_add_f32_e32 v216, v150, v216
	v_exp_f32_e32 v155, v155
	v_add_f32_e32 v216, v151, v216
	v_exp_f32_e32 v156, v156
	v_add_f32_e32 v216, v152, v216
	v_exp_f32_e32 v157, v157
	v_add_f32_e32 v216, v153, v216
	v_exp_f32_e32 v158, v158
	v_add_f32_e32 v216, v154, v216
	v_mul_f32_e32 v215, 0x3e0293ee, v215
	v_add_f32_e32 v216, v155, v216
	v_exp_f32_e32 v215, v215
	v_add_f32_e32 v216, v156, v216
	v_add_f32_e32 v216, v157, v216
	v_add_f32_e32 v216, v158, v216
	v_add_f32_e32 v216, v159, v216
	v_cndmask_b32_e64 v215, v215, 1.0, vcc
	v_mov_b32_e32 v217, v216
	v_cvt_pk_bf16_f32 v128, v128, v129
	v_cvt_pk_bf16_f32 v129, v130, v131
	v_cvt_pk_bf16_f32 v130, v132, v133
	v_cvt_pk_bf16_f32 v131, v134, v135
	v_cvt_pk_bf16_f32 v132, v136, v137
	v_cvt_pk_bf16_f32 v133, v138, v139
	v_cvt_pk_bf16_f32 v134, v140, v141
	v_cvt_pk_bf16_f32 v135, v142, v143
	v_cvt_pk_bf16_f32 v136, v144, v145
	v_cvt_pk_bf16_f32 v137, v146, v147
	v_cvt_pk_bf16_f32 v138, v148, v149
	v_cvt_pk_bf16_f32 v139, v150, v151
	v_cvt_pk_bf16_f32 v140, v152, v153
	v_cvt_pk_bf16_f32 v141, v154, v155
	v_cvt_pk_bf16_f32 v142, v156, v157
	v_cvt_pk_bf16_f32 v143, v158, v159
	s_nop 1
	v_permlane32_swap_b32_e32 v216, v217
	v_cmp_gt_f32_e32 vcc, 1.0, v215
	s_cbranch_vccz .LBB0_404
	s_and_saveexec_b64 s[56:57], s[4:5]
	ds_write_b32 v205, v215 offset:128
	s_or_b64 exec, exec, s[56:57]
	s_waitcnt lgkmcnt(0)
	v_add_u32_e32 v144, s63, v184
	ds_read_b128 v[156:159], v144 offset:224
	ds_read_b128 v[152:155], v144 offset:192
	ds_read_b128 v[148:151], v144 offset:160
	ds_read_b128 v[144:147], v144 offset:128
	s_waitcnt lgkmcnt(3)
	v_pk_mul_f32 v[76:77], v[76:77], v[156:157]
	s_waitcnt lgkmcnt(2)
	v_pk_mul_f32 v[72:73], v[72:73], v[152:153]
	s_waitcnt lgkmcnt(1)
	v_pk_mul_f32 v[68:69], v[68:69], v[148:149]
	v_pk_mul_f32 v[78:79], v[78:79], v[158:159]
	v_pk_mul_f32 v[74:75], v[74:75], v[154:155]
	v_pk_mul_f32 v[70:71], v[70:71], v[150:151]
	s_waitcnt lgkmcnt(0)
	v_pk_mul_f32 v[66:67], v[66:67], v[146:147]
	v_pk_mul_f32 v[64:65], v[64:65], v[144:145]
	v_pk_mul_f32 v[124:125], v[124:125], v[156:157]
	v_pk_mul_f32 v[120:121], v[120:121], v[152:153]
	v_pk_mul_f32 v[116:117], v[116:117], v[148:149]
	v_pk_mul_f32 v[126:127], v[126:127], v[158:159]
	v_pk_mul_f32 v[122:123], v[122:123], v[154:155]
	v_pk_mul_f32 v[118:119], v[118:119], v[150:151]
	v_pk_mul_f32 v[114:115], v[114:115], v[146:147]
	v_pk_mul_f32 v[112:113], v[112:113], v[144:145]
	v_pk_mul_f32 v[108:109], v[108:109], v[156:157]
	v_pk_mul_f32 v[104:105], v[104:105], v[152:153]
	v_pk_mul_f32 v[100:101], v[100:101], v[148:149]
	v_pk_mul_f32 v[110:111], v[110:111], v[158:159]
	v_pk_mul_f32 v[106:107], v[106:107], v[154:155]
	v_pk_mul_f32 v[102:103], v[102:103], v[150:151]
	v_pk_mul_f32 v[98:99], v[98:99], v[146:147]
	v_pk_mul_f32 v[96:97], v[96:97], v[144:145]
	v_pk_mul_f32 v[92:93], v[92:93], v[156:157]
	v_pk_mul_f32 v[88:89], v[88:89], v[152:153]
	v_pk_mul_f32 v[84:85], v[84:85], v[148:149]
	v_pk_mul_f32 v[94:95], v[94:95], v[158:159]
	v_pk_mul_f32 v[90:91], v[90:91], v[154:155]
	v_pk_mul_f32 v[86:87], v[86:87], v[150:151]
	v_pk_mul_f32 v[82:83], v[82:83], v[146:147]
	v_pk_mul_f32 v[80:81], v[80:81], v[144:145]
	v_pk_mul_f32 v[60:61], v[60:61], v[156:157]
	v_pk_mul_f32 v[56:57], v[56:57], v[152:153]
	v_pk_mul_f32 v[52:53], v[52:53], v[148:149]
	v_pk_mul_f32 v[62:63], v[62:63], v[158:159]
	v_pk_mul_f32 v[58:59], v[58:59], v[154:155]
	v_pk_mul_f32 v[54:55], v[54:55], v[150:151]
	v_pk_mul_f32 v[50:51], v[50:51], v[146:147]
	v_pk_mul_f32 v[48:49], v[48:49], v[144:145]
	v_pk_mul_f32 v[44:45], v[44:45], v[156:157]
	v_pk_mul_f32 v[40:41], v[40:41], v[152:153]
	v_pk_mul_f32 v[36:37], v[36:37], v[148:149]
	v_pk_mul_f32 v[46:47], v[46:47], v[158:159]
	v_pk_mul_f32 v[42:43], v[42:43], v[154:155]
	v_pk_mul_f32 v[38:39], v[38:39], v[150:151]
	v_pk_mul_f32 v[34:35], v[34:35], v[146:147]
	v_pk_mul_f32 v[32:33], v[32:33], v[144:145]
	v_pk_mul_f32 v[28:29], v[28:29], v[156:157]
	v_pk_mul_f32 v[24:25], v[24:25], v[152:153]
	v_pk_mul_f32 v[20:21], v[20:21], v[148:149]
	v_pk_mul_f32 v[30:31], v[30:31], v[158:159]
	v_pk_mul_f32 v[26:27], v[26:27], v[154:155]
	v_pk_mul_f32 v[22:23], v[22:23], v[150:151]
	v_pk_mul_f32 v[18:19], v[18:19], v[146:147]
	v_pk_mul_f32 v[16:17], v[16:17], v[144:145]
	v_pk_mul_f32 v[12:13], v[12:13], v[156:157]
	v_pk_mul_f32 v[8:9], v[8:9], v[152:153]
	v_pk_mul_f32 v[4:5], v[4:5], v[148:149]
	v_pk_mul_f32 v[14:15], v[14:15], v[158:159]
	v_pk_mul_f32 v[10:11], v[10:11], v[154:155]
	v_pk_mul_f32 v[6:7], v[6:7], v[150:151]
	v_pk_mul_f32 v[2:3], v[2:3], v[146:147]
	v_pk_mul_f32 v[0:1], v[0:1], v[144:145]
.LBB0_404:
	v_add_f32_e32 v230, v216, v217
	v_fmac_f32_e32 v230, v214, v215
	s_branch .Ldiff_sm_join
